# layer-1 weight copies (P2 tail): write-through sc1 stores, the buffer_wbl2 release write-back dropped
# speedup vs baseline: 1.0039x; 1.0039x over previous
.LBB0_508:
	s_lshl_b32 s8, s18, 6
	v_add_u32_e32 v31, s8, v17
	v_lshl_add_u64 v[32:33], s[6:7], 2, v[12:13]
	v_mad_i64_i32 v[34:35], s[18:19], v31, s16, v[32:33]
	v_add_u32_e32 v36, 2, v31
	v_add_u32_e32 v38, 4, v31
	v_add_u32_e32 v40, 6, v31
	v_add_u32_e32 v42, 8, v31
	v_add_u32_e32 v44, 10, v31
	v_add_u32_e32 v46, 12, v31
	v_add_u32_e32 v48, 14, v31
	v_mad_i64_i32 v[36:37], s[18:19], v36, s16, v[32:33]
	v_mad_i64_i32 v[38:39], s[18:19], v38, s16, v[32:33]
	v_mad_i64_i32 v[40:41], s[18:19], v40, s16, v[32:33]
	v_mad_i64_i32 v[42:43], s[18:19], v42, s16, v[32:33]
	v_mad_i64_i32 v[44:45], s[18:19], v44, s16, v[32:33]
	v_mad_i64_i32 v[46:47], s[18:19], v46, s16, v[32:33]
	v_mad_i64_i32 v[48:49], s[18:19], v48, s16, v[32:33]
	global_load_dword v50, v[34:35], off nt
	global_load_dword v51, v[36:37], off nt
	global_load_dword v52, v[38:39], off nt
	global_load_dword v53, v[40:41], off nt
	global_load_dword v54, v[42:43], off nt
	global_load_dword v55, v[44:45], off nt
	global_load_dword v56, v[46:47], off nt
	global_load_dword v57, v[48:49], off nt
	v_add_u32_e32 v34, 16, v31
	v_mad_i64_i32 v[34:35], s[18:19], v34, s16, v[32:33]
	v_add_u32_e32 v36, 18, v31
	v_add_u32_e32 v38, 20, v31
	v_add_u32_e32 v40, 22, v31
	v_add_u32_e32 v42, 24, v31
	v_add_u32_e32 v44, 26, v31
	v_add_u32_e32 v46, 28, v31
	v_add_u32_e32 v48, 30, v31
	v_mad_i64_i32 v[36:37], s[18:19], v36, s16, v[32:33]
	v_mad_i64_i32 v[38:39], s[18:19], v38, s16, v[32:33]
	v_mad_i64_i32 v[40:41], s[18:19], v40, s16, v[32:33]
	v_mad_i64_i32 v[42:43], s[18:19], v42, s16, v[32:33]
	v_mad_i64_i32 v[44:45], s[18:19], v44, s16, v[32:33]
	v_mad_i64_i32 v[46:47], s[18:19], v46, s16, v[32:33]
	v_mad_i64_i32 v[48:49], s[18:19], v48, s16, v[32:33]
	global_load_dword v58, v[34:35], off nt
	global_load_dword v59, v[36:37], off nt
	global_load_dword v60, v[38:39], off nt
	global_load_dword v61, v[40:41], off nt
	global_load_dword v62, v[42:43], off nt
	global_load_dword v63, v[44:45], off nt
	global_load_dword v64, v[46:47], off nt
	global_load_dword v65, v[48:49], off nt
	v_add_u32_e32 v34, 32, v31
	v_mad_i64_i32 v[34:35], s[18:19], v34, s16, v[32:33]
	v_add_u32_e32 v36, 34, v31
	v_add_u32_e32 v38, 36, v31
	v_add_u32_e32 v40, 38, v31
	v_add_u32_e32 v42, 40, v31
	v_add_u32_e32 v44, 42, v31
	v_add_u32_e32 v46, 44, v31
	v_add_u32_e32 v48, 46, v31
	v_mad_i64_i32 v[36:37], s[18:19], v36, s16, v[32:33]
	v_mad_i64_i32 v[38:39], s[18:19], v38, s16, v[32:33]
	v_mad_i64_i32 v[40:41], s[18:19], v40, s16, v[32:33]
	v_mad_i64_i32 v[42:43], s[18:19], v42, s16, v[32:33]
	v_mad_i64_i32 v[44:45], s[18:19], v44, s16, v[32:33]
	v_mad_i64_i32 v[46:47], s[18:19], v46, s16, v[32:33]
	v_mad_i64_i32 v[48:49], s[18:19], v48, s16, v[32:33]
	global_load_dword v66, v[34:35], off nt
	global_load_dword v67, v[36:37], off nt
	global_load_dword v68, v[38:39], off nt
	global_load_dword v69, v[40:41], off nt
	global_load_dword v70, v[42:43], off nt
	global_load_dword v71, v[44:45], off nt
	global_load_dword v72, v[46:47], off nt
	global_load_dword v73, v[48:49], off nt
	v_add_u32_e32 v34, 48, v31
	v_mad_i64_i32 v[34:35], s[18:19], v34, s16, v[32:33]
	v_add_u32_e32 v36, 50, v31
	v_add_u32_e32 v38, 52, v31
	v_add_u32_e32 v40, 54, v31
	v_add_u32_e32 v42, 56, v31
	v_add_u32_e32 v44, 58, v31
	v_add_u32_e32 v46, 60, v31
	v_add_u32_e32 v31, 62, v31
	v_mad_i64_i32 v[36:37], s[18:19], v36, s16, v[32:33]
	v_mad_i64_i32 v[38:39], s[18:19], v38, s16, v[32:33]
	v_mad_i64_i32 v[40:41], s[18:19], v40, s16, v[32:33]
	v_mad_i64_i32 v[42:43], s[18:19], v42, s16, v[32:33]
	v_mad_i64_i32 v[44:45], s[18:19], v44, s16, v[32:33]
	v_mad_i64_i32 v[46:47], s[18:19], v46, s16, v[32:33]
	v_mad_i64_i32 v[32:33], s[18:19], v31, s16, v[32:33]
	global_load_dword v31, v[34:35], off nt
	global_load_dword v48, v[36:37], off nt
	global_load_dword v49, v[38:39], off nt
	global_load_dword v74, v[40:41], off nt
	global_load_dword v75, v[42:43], off nt
	global_load_dword v76, v[44:45], off nt
	global_load_dword v77, v[46:47], off nt
	global_load_dword v78, v[32:33], off nt
	s_waitcnt vmcnt(0)
	ds_write2_b32 v18, v50, v51 offset1:66
	ds_write2_b32 v18, v52, v53 offset0:132 offset1:198
	ds_write2_b32 v24, v54, v55 offset0:8 offset1:74
	ds_write2_b32 v24, v56, v57 offset0:140 offset1:206
	ds_write2_b32 v25, v58, v59 offset0:16 offset1:82
	ds_write2_b32 v25, v60, v61 offset0:148 offset1:214
	ds_write2_b32 v26, v62, v63 offset0:24 offset1:90
	ds_write2_b32 v26, v64, v65 offset0:156 offset1:222
	ds_write2_b32 v27, v66, v67 offset0:32 offset1:98
	ds_write2_b32 v27, v68, v69 offset0:164 offset1:230
	ds_write2_b32 v28, v70, v71 offset0:40 offset1:106
	ds_write2_b32 v28, v72, v73 offset0:172 offset1:238
	ds_write2_b32 v29, v31, v48 offset0:48 offset1:114
	ds_write2_b32 v29, v49, v74 offset0:180 offset1:246
	ds_write2_b32 v30, v75, v76 offset0:56 offset1:122
	ds_write2_b32 v30, v77, v78 offset0:188 offset1:254
	s_waitcnt lgkmcnt(0)
	ds_read2_b32 v[36:37], v20 offset0:33 offset1:41
	ds_read2_b32 v[38:39], v20 offset1:8
	ds_read2_b32 v[40:41], v20 offset0:66 offset1:74
	ds_read2_b32 v[42:43], v20 offset0:99 offset1:107
	ds_read2_b32 v[44:45], v20 offset0:132 offset1:140
	ds_read2_b32 v[46:47], v20 offset0:165 offset1:173
	ds_read2_b32 v[48:49], v20 offset0:198 offset1:206
	ds_read2_b32 v[50:51], v20 offset0:231 offset1:239
	s_add_i32 s6, s10, s17
	v_add_u32_e32 v31, s6, v19
	v_add_u32_e32 v54, 0x600, v31
	s_ashr_i32 s9, s8, 31
	v_ashrrev_i32_e32 v55, 31, v54
	v_lshl_add_u64 v[52:53], s[8:9], 1, v[14:15]
	v_lshlrev_b64 v[54:55], 11, v[54:55]
	s_waitcnt lgkmcnt(6)
	v_cvt_pk_bf16_f32 v32, v38, v36
	s_waitcnt lgkmcnt(4)
	v_cvt_pk_bf16_f32 v33, v40, v42
	s_waitcnt lgkmcnt(2)
	v_cvt_pk_bf16_f32 v34, v44, v46
	s_waitcnt lgkmcnt(0)
	v_cvt_pk_bf16_f32 v35, v48, v50
	v_lshl_add_u64 v[54:55], v[52:53], 0, v[54:55]
	v_add_u32_e32 v36, 0x608, v31
	global_store_dwordx4 v[54:55], v[32:35], off sc1
	s_nop 1
	v_cvt_pk_bf16_f32 v32, v39, v37
	v_ashrrev_i32_e32 v37, 31, v36
	v_cvt_pk_bf16_f32 v33, v41, v43
	v_cvt_pk_bf16_f32 v34, v45, v47
	v_cvt_pk_bf16_f32 v35, v49, v51
	v_lshlrev_b64 v[36:37], 11, v[36:37]
	ds_read2_b32 v[38:39], v20 offset0:49 offset1:57
	ds_read2_b32 v[40:41], v20 offset0:16 offset1:24
	ds_read2_b32 v[42:43], v20 offset0:82 offset1:90
	ds_read2_b32 v[44:45], v20 offset0:115 offset1:123
	ds_read2_b32 v[46:47], v20 offset0:148 offset1:156
	ds_read2_b32 v[48:49], v20 offset0:181 offset1:189
	ds_read2_b32 v[50:51], v20 offset0:214 offset1:222
	ds_read2_b32 v[54:55], v20 offset0:247 offset1:255
	v_lshl_add_u64 v[36:37], v[52:53], 0, v[36:37]
	global_store_dwordx4 v[36:37], v[32:35], off sc1
	v_add_u32_e32 v36, 0x610, v31
	v_ashrrev_i32_e32 v37, 31, v36
	v_lshlrev_b64 v[36:37], 11, v[36:37]
	s_waitcnt lgkmcnt(6)
	v_cvt_pk_bf16_f32 v32, v40, v38
	s_waitcnt lgkmcnt(4)
	v_cvt_pk_bf16_f32 v33, v42, v44
	s_waitcnt lgkmcnt(2)
	v_cvt_pk_bf16_f32 v34, v46, v48
	s_waitcnt lgkmcnt(0)
	v_cvt_pk_bf16_f32 v35, v50, v54
	v_lshl_add_u64 v[36:37], v[52:53], 0, v[36:37]
	global_store_dwordx4 v[36:37], v[32:35], off sc1
	v_add_u32_e32 v36, 0x618, v31
	v_ashrrev_i32_e32 v37, 31, v36
	v_lshlrev_b64 v[36:37], 11, v[36:37]
	v_cvt_pk_bf16_f32 v32, v41, v39
	v_cvt_pk_bf16_f32 v33, v43, v45
	v_cvt_pk_bf16_f32 v34, v47, v49
	v_cvt_pk_bf16_f32 v35, v51, v55
	v_lshl_add_u64 v[36:37], v[52:53], 0, v[36:37]
	global_store_dwordx4 v[36:37], v[32:35], off sc1
	s_waitcnt lgkmcnt(0)

.LBB0_510:
	s_cmpk_gt_i32 s3, 0x8ff
	s_mov_b64 s[8:9], -1
	s_cbranch_scc0 .LBB0_532
	s_cmpk_gt_u32 s3, 0xaff
	s_cbranch_scc0 .LBB0_529
	s_cmpk_gt_u32 s3, 0x11ff
	s_cbranch_scc0 .LBB0_514
	s_add_i32 s6, s10, 0x600
	s_and_b32 s17, s6, 0x3e0
	s_and_b32 s6, s12, 0x3fc0
	s_add_i32 s8, s6, 0xffffdc00
	v_add_u32_e32 v32, s8, v17
	s_lshl_b32 s6, s17, 2
	v_ashrrev_i32_e32 v33, 31, v32
	v_lshl_add_u64 v[34:35], v[0:1], 0, s[6:7]
	v_lshlrev_b64 v[32:33], 12, v[32:33]
	v_lshl_add_u64 v[32:33], v[34:35], 0, v[32:33]
	v_add_co_u32_e32 v34, vcc, 0x2000, v32
	s_mov_b32 s9, s7
	s_nop 0
	v_addc_co_u32_e32 v35, vcc, 0, v33, vcc
	v_add_co_u32_e32 v36, vcc, 0x4000, v32
	s_nop 1
	v_addc_co_u32_e32 v37, vcc, 0, v33, vcc
	v_add_co_u32_e32 v38, vcc, 0x6000, v32
	s_nop 1
	v_addc_co_u32_e32 v39, vcc, 0, v33, vcc
	v_add_co_u32_e32 v40, vcc, 0x8000, v32
	s_nop 1
	v_addc_co_u32_e32 v41, vcc, 0, v33, vcc
	v_add_co_u32_e32 v42, vcc, 0xa000, v32
	s_nop 1
	v_addc_co_u32_e32 v43, vcc, 0, v33, vcc
	v_add_co_u32_e32 v44, vcc, 0xc000, v32
	s_nop 1
	v_addc_co_u32_e32 v45, vcc, 0, v33, vcc
	v_add_co_u32_e32 v46, vcc, 0xe000, v32
	s_nop 1
	v_addc_co_u32_e32 v47, vcc, 0, v33, vcc
	global_load_dword v31, v[32:33], off nt
	global_load_dword v50, v[34:35], off nt
	global_load_dword v51, v[36:37], off nt
	global_load_dword v52, v[38:39], off nt
	global_load_dword v53, v[40:41], off nt
	global_load_dword v54, v[42:43], off nt
	global_load_dword v55, v[44:45], off nt
	global_load_dword v56, v[46:47], off nt
	v_add_co_u32_e32 v34, vcc, 0x10000, v32
	s_nop 1
	v_addc_co_u32_e32 v35, vcc, 0, v33, vcc
	v_add_co_u32_e32 v36, vcc, 0x12000, v32
	s_nop 1
	v_addc_co_u32_e32 v37, vcc, 0, v33, vcc
	v_add_co_u32_e32 v38, vcc, 0x14000, v32
	s_nop 1
	v_addc_co_u32_e32 v39, vcc, 0, v33, vcc
	v_add_co_u32_e32 v40, vcc, 0x16000, v32
	s_nop 1
	v_addc_co_u32_e32 v41, vcc, 0, v33, vcc
	v_add_co_u32_e32 v42, vcc, 0x18000, v32
	s_nop 1
	v_addc_co_u32_e32 v43, vcc, 0, v33, vcc
	v_add_co_u32_e32 v44, vcc, 0x1a000, v32
	s_nop 1
	v_addc_co_u32_e32 v45, vcc, 0, v33, vcc
	v_add_co_u32_e32 v46, vcc, 0x1c000, v32
	s_nop 1
	v_addc_co_u32_e32 v47, vcc, 0, v33, vcc
	v_add_co_u32_e32 v48, vcc, 0x1e000, v32
	s_nop 1
	v_addc_co_u32_e32 v49, vcc, 0, v33, vcc
	global_load_dword v57, v[34:35], off nt
	global_load_dword v58, v[36:37], off nt
	global_load_dword v59, v[38:39], off nt
	global_load_dword v60, v[40:41], off nt
	global_load_dword v61, v[42:43], off nt
	global_load_dword v62, v[44:45], off nt
	global_load_dword v63, v[46:47], off nt
	global_load_dword v64, v[48:49], off nt
	v_add_co_u32_e32 v34, vcc, 0x20000, v32
	s_nop 1
	v_addc_co_u32_e32 v35, vcc, 0, v33, vcc
	v_add_co_u32_e32 v36, vcc, 0x22000, v32
	s_nop 1
	v_addc_co_u32_e32 v37, vcc, 0, v33, vcc
	v_add_co_u32_e32 v38, vcc, 0x24000, v32
	s_nop 1
	v_addc_co_u32_e32 v39, vcc, 0, v33, vcc
	v_add_co_u32_e32 v40, vcc, 0x26000, v32
	s_nop 1
	v_addc_co_u32_e32 v41, vcc, 0, v33, vcc
	v_add_co_u32_e32 v42, vcc, 0x28000, v32
	s_nop 1
	v_addc_co_u32_e32 v43, vcc, 0, v33, vcc
	v_add_co_u32_e32 v44, vcc, 0x2a000, v32
	s_nop 1
	v_addc_co_u32_e32 v45, vcc, 0, v33, vcc
	v_add_co_u32_e32 v46, vcc, 0x2c000, v32
	s_nop 1
	v_addc_co_u32_e32 v47, vcc, 0, v33, vcc
	v_add_co_u32_e32 v48, vcc, 0x2e000, v32
	s_nop 1
	v_addc_co_u32_e32 v49, vcc, 0, v33, vcc
	global_load_dword v65, v[34:35], off nt
	global_load_dword v66, v[36:37], off nt
	global_load_dword v67, v[38:39], off nt
	global_load_dword v68, v[40:41], off nt
	global_load_dword v69, v[42:43], off nt
	global_load_dword v70, v[44:45], off nt
	global_load_dword v71, v[46:47], off nt
	global_load_dword v72, v[48:49], off nt
	v_add_co_u32_e32 v34, vcc, 0x30000, v32
	s_nop 1
	v_addc_co_u32_e32 v35, vcc, 0, v33, vcc
	v_add_co_u32_e32 v36, vcc, 0x32000, v32
	s_nop 1
	v_addc_co_u32_e32 v37, vcc, 0, v33, vcc
	v_add_co_u32_e32 v38, vcc, 0x34000, v32
	s_nop 1
	v_addc_co_u32_e32 v39, vcc, 0, v33, vcc
	v_add_co_u32_e32 v40, vcc, 0x36000, v32
	s_nop 1
	v_addc_co_u32_e32 v41, vcc, 0, v33, vcc
	v_add_co_u32_e32 v42, vcc, 0x38000, v32
	s_nop 1
	v_addc_co_u32_e32 v43, vcc, 0, v33, vcc
	v_add_co_u32_e32 v44, vcc, 0x3a000, v32
	s_nop 1
	v_addc_co_u32_e32 v45, vcc, 0, v33, vcc
	v_add_co_u32_e32 v46, vcc, 0x3c000, v32
	s_nop 1
	v_addc_co_u32_e32 v47, vcc, 0, v33, vcc
	v_add_co_u32_e32 v32, vcc, 0x3e000, v32
	s_nop 1
	v_addc_co_u32_e32 v33, vcc, 0, v33, vcc
	global_load_dword v48, v[34:35], off nt
	global_load_dword v49, v[36:37], off nt
	global_load_dword v73, v[38:39], off nt
	global_load_dword v74, v[40:41], off nt
	global_load_dword v75, v[42:43], off nt
	global_load_dword v76, v[44:45], off nt
	global_load_dword v77, v[46:47], off nt
	global_load_dword v78, v[32:33], off nt
	s_waitcnt vmcnt(0)
	ds_write2_b32 v18, v31, v50 offset1:66
	ds_write2_b32 v18, v51, v52 offset0:132 offset1:198
	ds_write2_b32 v24, v53, v54 offset0:8 offset1:74
	ds_write2_b32 v24, v55, v56 offset0:140 offset1:206
	ds_write2_b32 v25, v57, v58 offset0:16 offset1:82
	ds_write2_b32 v25, v59, v60 offset0:148 offset1:214
	ds_write2_b32 v26, v61, v62 offset0:24 offset1:90
	ds_write2_b32 v26, v63, v64 offset0:156 offset1:222
	ds_write2_b32 v27, v65, v66 offset0:32 offset1:98
	ds_write2_b32 v27, v67, v68 offset0:164 offset1:230
	ds_write2_b32 v28, v69, v70 offset0:40 offset1:106
	ds_write2_b32 v28, v71, v72 offset0:172 offset1:238
	ds_write2_b32 v29, v48, v49 offset0:48 offset1:114
	ds_write2_b32 v29, v73, v74 offset0:180 offset1:246
	ds_write2_b32 v30, v75, v76 offset0:56 offset1:122
	ds_write2_b32 v30, v77, v78 offset0:188 offset1:254
	s_waitcnt lgkmcnt(0)
	ds_read2_b32 v[36:37], v20 offset0:33 offset1:41
	ds_read2_b32 v[38:39], v20 offset1:8
	ds_read2_b32 v[40:41], v20 offset0:66 offset1:74
	ds_read2_b32 v[42:43], v20 offset0:99 offset1:107
	ds_read2_b32 v[44:45], v20 offset0:132 offset1:140
	ds_read2_b32 v[46:47], v20 offset0:165 offset1:173
	ds_read2_b32 v[48:49], v20 offset0:198 offset1:206
	ds_read2_b32 v[50:51], v20 offset0:231 offset1:239
	v_add_u32_e32 v54, s17, v19
	v_ashrrev_i32_e32 v55, 31, v54
	v_lshl_add_u64 v[52:53], s[8:9], 1, v[2:3]
	v_lshlrev_b64 v[54:55], 11, v[54:55]
	s_waitcnt lgkmcnt(6)
	v_cvt_pk_bf16_f32 v32, v38, v36
	s_waitcnt lgkmcnt(4)
	v_cvt_pk_bf16_f32 v33, v40, v42
	s_waitcnt lgkmcnt(2)
	v_cvt_pk_bf16_f32 v34, v44, v46
	s_waitcnt lgkmcnt(0)
	v_cvt_pk_bf16_f32 v35, v48, v50
	v_lshl_add_u64 v[54:55], v[52:53], 0, v[54:55]
	v_add_u32_e32 v36, s17, v21
	global_store_dwordx4 v[54:55], v[32:35], off sc1
	s_mov_b64 s[8:9], 0
	s_nop 0
	v_cvt_pk_bf16_f32 v32, v39, v37
	v_ashrrev_i32_e32 v37, 31, v36
	v_cvt_pk_bf16_f32 v33, v41, v43
	v_cvt_pk_bf16_f32 v34, v45, v47
	v_cvt_pk_bf16_f32 v35, v49, v51
	v_lshlrev_b64 v[36:37], 11, v[36:37]
	ds_read2_b32 v[38:39], v20 offset0:49 offset1:57
	ds_read2_b32 v[40:41], v20 offset0:16 offset1:24
	ds_read2_b32 v[42:43], v20 offset0:82 offset1:90
	ds_read2_b32 v[44:45], v20 offset0:115 offset1:123
	ds_read2_b32 v[46:47], v20 offset0:148 offset1:156
	ds_read2_b32 v[48:49], v20 offset0:181 offset1:189
	ds_read2_b32 v[50:51], v20 offset0:214 offset1:222
	ds_read2_b32 v[54:55], v20 offset0:247 offset1:255
	v_lshl_add_u64 v[36:37], v[52:53], 0, v[36:37]
	global_store_dwordx4 v[36:37], v[32:35], off sc1
	v_add_u32_e32 v36, s17, v22
	v_ashrrev_i32_e32 v37, 31, v36
	v_lshlrev_b64 v[36:37], 11, v[36:37]
	s_waitcnt lgkmcnt(6)
	v_cvt_pk_bf16_f32 v32, v40, v38
	s_waitcnt lgkmcnt(4)
	v_cvt_pk_bf16_f32 v33, v42, v44
	s_waitcnt lgkmcnt(2)
	v_cvt_pk_bf16_f32 v34, v46, v48
	s_waitcnt lgkmcnt(0)
	v_cvt_pk_bf16_f32 v35, v50, v54
	v_lshl_add_u64 v[36:37], v[52:53], 0, v[36:37]
	global_store_dwordx4 v[36:37], v[32:35], off sc1
	v_add_u32_e32 v36, s17, v23
	v_ashrrev_i32_e32 v37, 31, v36
	v_lshlrev_b64 v[36:37], 11, v[36:37]
	v_cvt_pk_bf16_f32 v32, v41, v39
	v_cvt_pk_bf16_f32 v33, v43, v45
	v_cvt_pk_bf16_f32 v34, v47, v49
	v_cvt_pk_bf16_f32 v35, v51, v55
	v_lshl_add_u64 v[36:37], v[52:53], 0, v[36:37]
	global_store_dwordx4 v[36:37], v[32:35], off sc1
	s_waitcnt lgkmcnt(0)

.LBB0_527:
	s_lshl_b32 s8, s18, 6
	s_and_b32 s18, s8, 0xffc0
	v_add_u32_e32 v31, s18, v17
	v_lshl_add_u64 v[32:33], s[6:7], 2, v[4:5]
	v_mad_i64_i32 v[34:35], s[8:9], v31, s15, v[32:33]
	v_add_u32_e32 v36, 2, v31
	v_add_u32_e32 v38, 4, v31
	v_add_u32_e32 v40, 6, v31
	v_add_u32_e32 v42, 8, v31
	v_add_u32_e32 v44, 10, v31
	v_add_u32_e32 v46, 12, v31
	v_add_u32_e32 v48, 14, v31
	v_mad_i64_i32 v[36:37], s[8:9], v36, s15, v[32:33]
	v_mad_i64_i32 v[38:39], s[8:9], v38, s15, v[32:33]
	v_mad_i64_i32 v[40:41], s[8:9], v40, s15, v[32:33]
	v_mad_i64_i32 v[42:43], s[8:9], v42, s15, v[32:33]
	v_mad_i64_i32 v[44:45], s[8:9], v44, s15, v[32:33]
	v_mad_i64_i32 v[46:47], s[8:9], v46, s15, v[32:33]
	v_mad_i64_i32 v[48:49], s[8:9], v48, s15, v[32:33]
	global_load_dword v50, v[34:35], off nt
	global_load_dword v51, v[36:37], off nt
	global_load_dword v52, v[38:39], off nt
	global_load_dword v53, v[40:41], off nt
	global_load_dword v54, v[42:43], off nt
	global_load_dword v55, v[44:45], off nt
	global_load_dword v56, v[46:47], off nt
	global_load_dword v57, v[48:49], off nt
	v_add_u32_e32 v34, 16, v31
	v_mad_i64_i32 v[34:35], s[8:9], v34, s15, v[32:33]
	v_add_u32_e32 v36, 18, v31
	v_add_u32_e32 v38, 20, v31
	v_add_u32_e32 v40, 22, v31
	v_add_u32_e32 v42, 24, v31
	v_add_u32_e32 v44, 26, v31
	v_add_u32_e32 v46, 28, v31
	v_add_u32_e32 v48, 30, v31
	v_mad_i64_i32 v[36:37], s[8:9], v36, s15, v[32:33]
	v_mad_i64_i32 v[38:39], s[8:9], v38, s15, v[32:33]
	v_mad_i64_i32 v[40:41], s[8:9], v40, s15, v[32:33]
	v_mad_i64_i32 v[42:43], s[8:9], v42, s15, v[32:33]
	v_mad_i64_i32 v[44:45], s[8:9], v44, s15, v[32:33]
	v_mad_i64_i32 v[46:47], s[8:9], v46, s15, v[32:33]
	v_mad_i64_i32 v[48:49], s[8:9], v48, s15, v[32:33]
	global_load_dword v58, v[34:35], off nt
	global_load_dword v59, v[36:37], off nt
	global_load_dword v60, v[38:39], off nt
	global_load_dword v61, v[40:41], off nt
	global_load_dword v62, v[42:43], off nt
	global_load_dword v63, v[44:45], off nt
	global_load_dword v64, v[46:47], off nt
	global_load_dword v65, v[48:49], off nt
	v_add_u32_e32 v34, 32, v31
	v_mad_i64_i32 v[34:35], s[8:9], v34, s15, v[32:33]
	v_add_u32_e32 v36, 34, v31
	v_add_u32_e32 v38, 36, v31
	v_add_u32_e32 v40, 38, v31
	v_add_u32_e32 v42, 40, v31
	v_add_u32_e32 v44, 42, v31
	v_add_u32_e32 v46, 44, v31
	v_add_u32_e32 v48, 46, v31
	v_mad_i64_i32 v[36:37], s[8:9], v36, s15, v[32:33]
	v_mad_i64_i32 v[38:39], s[8:9], v38, s15, v[32:33]
	v_mad_i64_i32 v[40:41], s[8:9], v40, s15, v[32:33]
	v_mad_i64_i32 v[42:43], s[8:9], v42, s15, v[32:33]
	v_mad_i64_i32 v[44:45], s[8:9], v44, s15, v[32:33]
	v_mad_i64_i32 v[46:47], s[8:9], v46, s15, v[32:33]
	v_mad_i64_i32 v[48:49], s[8:9], v48, s15, v[32:33]
	global_load_dword v66, v[34:35], off nt
	global_load_dword v67, v[36:37], off nt
	global_load_dword v68, v[38:39], off nt
	global_load_dword v69, v[40:41], off nt
	global_load_dword v70, v[42:43], off nt
	global_load_dword v71, v[44:45], off nt
	global_load_dword v72, v[46:47], off nt
	global_load_dword v73, v[48:49], off nt
	v_add_u32_e32 v34, 48, v31
	v_mad_i64_i32 v[34:35], s[8:9], v34, s15, v[32:33]
	v_add_u32_e32 v36, 50, v31
	v_add_u32_e32 v38, 52, v31
	v_add_u32_e32 v40, 54, v31
	v_add_u32_e32 v42, 56, v31
	v_add_u32_e32 v44, 58, v31
	v_add_u32_e32 v46, 60, v31
	v_add_u32_e32 v31, 62, v31
	v_mad_i64_i32 v[36:37], s[8:9], v36, s15, v[32:33]
	v_mad_i64_i32 v[38:39], s[8:9], v38, s15, v[32:33]
	v_mad_i64_i32 v[40:41], s[8:9], v40, s15, v[32:33]
	v_mad_i64_i32 v[42:43], s[8:9], v42, s15, v[32:33]
	v_mad_i64_i32 v[44:45], s[8:9], v44, s15, v[32:33]
	v_mad_i64_i32 v[46:47], s[8:9], v46, s15, v[32:33]
	v_mad_i64_i32 v[32:33], s[8:9], v31, s15, v[32:33]
	global_load_dword v31, v[34:35], off nt
	global_load_dword v48, v[36:37], off nt
	global_load_dword v49, v[38:39], off nt
	global_load_dword v74, v[40:41], off nt
	global_load_dword v75, v[42:43], off nt
	global_load_dword v76, v[44:45], off nt
	global_load_dword v77, v[46:47], off nt
	global_load_dword v78, v[32:33], off nt
	s_waitcnt vmcnt(0)
	ds_write2_b32 v18, v50, v51 offset1:66
	ds_write2_b32 v18, v52, v53 offset0:132 offset1:198
	ds_write2_b32 v24, v54, v55 offset0:8 offset1:74
	ds_write2_b32 v24, v56, v57 offset0:140 offset1:206
	ds_write2_b32 v25, v58, v59 offset0:16 offset1:82
	ds_write2_b32 v25, v60, v61 offset0:148 offset1:214
	ds_write2_b32 v26, v62, v63 offset0:24 offset1:90
	ds_write2_b32 v26, v64, v65 offset0:156 offset1:222
	ds_write2_b32 v27, v66, v67 offset0:32 offset1:98
	ds_write2_b32 v27, v68, v69 offset0:164 offset1:230
	ds_write2_b32 v28, v70, v71 offset0:40 offset1:106
	ds_write2_b32 v28, v72, v73 offset0:172 offset1:238
	ds_write2_b32 v29, v31, v48 offset0:48 offset1:114
	ds_write2_b32 v29, v49, v74 offset0:180 offset1:246
	ds_write2_b32 v30, v75, v76 offset0:56 offset1:122
	ds_write2_b32 v30, v77, v78 offset0:188 offset1:254
	s_waitcnt lgkmcnt(0)
	ds_read2_b32 v[36:37], v20 offset0:33 offset1:41
	ds_read2_b32 v[38:39], v20 offset1:8
	ds_read2_b32 v[40:41], v20 offset0:66 offset1:74
	ds_read2_b32 v[42:43], v20 offset0:99 offset1:107
	ds_read2_b32 v[44:45], v20 offset0:132 offset1:140
	ds_read2_b32 v[46:47], v20 offset0:165 offset1:173
	ds_read2_b32 v[48:49], v20 offset0:198 offset1:206
	ds_read2_b32 v[50:51], v20 offset0:231 offset1:239
	v_add_u32_e32 v54, s17, v19
	s_lshl_b32 s6, s18, 1
	v_ashrrev_i32_e32 v55, 31, v54
	v_lshl_add_u64 v[52:53], v[6:7], 0, s[6:7]
	v_lshlrev_b64 v[54:55], 11, v[54:55]
	s_waitcnt lgkmcnt(6)
	v_cvt_pk_bf16_f32 v32, v38, v36
	s_waitcnt lgkmcnt(4)
	v_cvt_pk_bf16_f32 v33, v40, v42
	s_waitcnt lgkmcnt(2)
	v_cvt_pk_bf16_f32 v34, v44, v46
	s_waitcnt lgkmcnt(0)
	v_cvt_pk_bf16_f32 v35, v48, v50
	v_lshl_add_u64 v[54:55], v[52:53], 0, v[54:55]
	v_add_u32_e32 v36, s17, v21
	global_store_dwordx4 v[54:55], v[32:35], off sc1
	s_nop 1
	v_cvt_pk_bf16_f32 v32, v39, v37
	v_ashrrev_i32_e32 v37, 31, v36
	v_cvt_pk_bf16_f32 v33, v41, v43
	v_cvt_pk_bf16_f32 v34, v45, v47
	v_cvt_pk_bf16_f32 v35, v49, v51
	v_lshlrev_b64 v[36:37], 11, v[36:37]
	ds_read2_b32 v[38:39], v20 offset0:49 offset1:57
	ds_read2_b32 v[40:41], v20 offset0:16 offset1:24
	ds_read2_b32 v[42:43], v20 offset0:82 offset1:90
	ds_read2_b32 v[44:45], v20 offset0:115 offset1:123
	ds_read2_b32 v[46:47], v20 offset0:148 offset1:156
	ds_read2_b32 v[48:49], v20 offset0:181 offset1:189
	ds_read2_b32 v[50:51], v20 offset0:214 offset1:222
	ds_read2_b32 v[54:55], v20 offset0:247 offset1:255
	v_lshl_add_u64 v[36:37], v[52:53], 0, v[36:37]
	global_store_dwordx4 v[36:37], v[32:35], off sc1
	v_add_u32_e32 v36, s17, v22
	v_ashrrev_i32_e32 v37, 31, v36
	v_lshlrev_b64 v[36:37], 11, v[36:37]
	s_waitcnt lgkmcnt(6)
	v_cvt_pk_bf16_f32 v32, v40, v38
	s_waitcnt lgkmcnt(4)
	v_cvt_pk_bf16_f32 v33, v42, v44
	s_waitcnt lgkmcnt(2)
	v_cvt_pk_bf16_f32 v34, v46, v48
	s_waitcnt lgkmcnt(0)
	v_cvt_pk_bf16_f32 v35, v50, v54
	v_lshl_add_u64 v[36:37], v[52:53], 0, v[36:37]
	global_store_dwordx4 v[36:37], v[32:35], off sc1
	v_add_u32_e32 v36, s17, v23
	v_ashrrev_i32_e32 v37, 31, v36
	v_lshlrev_b64 v[36:37], 11, v[36:37]
	v_cvt_pk_bf16_f32 v32, v41, v39
	v_cvt_pk_bf16_f32 v33, v43, v45
	v_cvt_pk_bf16_f32 v34, v47, v49
	v_cvt_pk_bf16_f32 v35, v51, v55
	v_lshl_add_u64 v[36:37], v[52:53], 0, v[36:37]
	global_store_dwordx4 v[36:37], v[32:35], off sc1
	s_waitcnt lgkmcnt(0)

.LBB0_529:
	s_andn2_b64 vcc, exec, s[8:9]
	s_cbranch_vccnz .LBB0_531
	s_add_i32 s6, s10, 0x600
	s_and_b32 s17, s6, 0x3e0
	s_and_b32 s6, s12, 0x1fc0
	s_add_i32 s8, s6, 0xffffee00
	v_add_u32_e32 v32, s8, v17
	s_lshl_b32 s6, s17, 2
	v_ashrrev_i32_e32 v33, 31, v32
	v_lshl_add_u64 v[34:35], v[8:9], 0, s[6:7]
	v_lshlrev_b64 v[32:33], 12, v[32:33]
	v_lshl_add_u64 v[32:33], v[34:35], 0, v[32:33]
	v_add_co_u32_e32 v34, vcc, 0x2000, v32
	s_mov_b32 s9, s7
	s_nop 0
	v_addc_co_u32_e32 v35, vcc, 0, v33, vcc
	v_add_co_u32_e32 v36, vcc, 0x4000, v32
	s_nop 1
	v_addc_co_u32_e32 v37, vcc, 0, v33, vcc
	v_add_co_u32_e32 v38, vcc, 0x6000, v32
	s_nop 1
	v_addc_co_u32_e32 v39, vcc, 0, v33, vcc
	v_add_co_u32_e32 v40, vcc, 0x8000, v32
	s_nop 1
	v_addc_co_u32_e32 v41, vcc, 0, v33, vcc
	v_add_co_u32_e32 v42, vcc, 0xa000, v32
	s_nop 1
	v_addc_co_u32_e32 v43, vcc, 0, v33, vcc
	v_add_co_u32_e32 v44, vcc, 0xc000, v32
	s_nop 1
	v_addc_co_u32_e32 v45, vcc, 0, v33, vcc
	v_add_co_u32_e32 v46, vcc, 0xe000, v32
	s_nop 1
	v_addc_co_u32_e32 v47, vcc, 0, v33, vcc
	global_load_dword v31, v[32:33], off nt
	global_load_dword v50, v[34:35], off nt
	global_load_dword v51, v[36:37], off nt
	global_load_dword v52, v[38:39], off nt
	global_load_dword v53, v[40:41], off nt
	global_load_dword v54, v[42:43], off nt
	global_load_dword v55, v[44:45], off nt
	global_load_dword v56, v[46:47], off nt
	v_add_co_u32_e32 v34, vcc, 0x10000, v32
	s_nop 1
	v_addc_co_u32_e32 v35, vcc, 0, v33, vcc
	v_add_co_u32_e32 v36, vcc, 0x12000, v32
	s_nop 1
	v_addc_co_u32_e32 v37, vcc, 0, v33, vcc
	v_add_co_u32_e32 v38, vcc, 0x14000, v32
	s_nop 1
	v_addc_co_u32_e32 v39, vcc, 0, v33, vcc
	v_add_co_u32_e32 v40, vcc, 0x16000, v32
	s_nop 1
	v_addc_co_u32_e32 v41, vcc, 0, v33, vcc
	v_add_co_u32_e32 v42, vcc, 0x18000, v32
	s_nop 1
	v_addc_co_u32_e32 v43, vcc, 0, v33, vcc
	v_add_co_u32_e32 v44, vcc, 0x1a000, v32
	s_nop 1
	v_addc_co_u32_e32 v45, vcc, 0, v33, vcc
	v_add_co_u32_e32 v46, vcc, 0x1c000, v32
	s_nop 1
	v_addc_co_u32_e32 v47, vcc, 0, v33, vcc
	v_add_co_u32_e32 v48, vcc, 0x1e000, v32
	s_nop 1
	v_addc_co_u32_e32 v49, vcc, 0, v33, vcc
	global_load_dword v57, v[34:35], off nt
	global_load_dword v58, v[36:37], off nt
	global_load_dword v59, v[38:39], off nt
	global_load_dword v60, v[40:41], off nt
	global_load_dword v61, v[42:43], off nt
	global_load_dword v62, v[44:45], off nt
	global_load_dword v63, v[46:47], off nt
	global_load_dword v64, v[48:49], off nt
	v_add_co_u32_e32 v34, vcc, 0x20000, v32
	s_nop 1
	v_addc_co_u32_e32 v35, vcc, 0, v33, vcc
	v_add_co_u32_e32 v36, vcc, 0x22000, v32
	s_nop 1
	v_addc_co_u32_e32 v37, vcc, 0, v33, vcc
	v_add_co_u32_e32 v38, vcc, 0x24000, v32
	s_nop 1
	v_addc_co_u32_e32 v39, vcc, 0, v33, vcc
	v_add_co_u32_e32 v40, vcc, 0x26000, v32
	s_nop 1
	v_addc_co_u32_e32 v41, vcc, 0, v33, vcc
	v_add_co_u32_e32 v42, vcc, 0x28000, v32
	s_nop 1
	v_addc_co_u32_e32 v43, vcc, 0, v33, vcc
	v_add_co_u32_e32 v44, vcc, 0x2a000, v32
	s_nop 1
	v_addc_co_u32_e32 v45, vcc, 0, v33, vcc
	v_add_co_u32_e32 v46, vcc, 0x2c000, v32
	s_nop 1
	v_addc_co_u32_e32 v47, vcc, 0, v33, vcc
	v_add_co_u32_e32 v48, vcc, 0x2e000, v32
	s_nop 1
	v_addc_co_u32_e32 v49, vcc, 0, v33, vcc
	global_load_dword v65, v[34:35], off nt
	global_load_dword v66, v[36:37], off nt
	global_load_dword v67, v[38:39], off nt
	global_load_dword v68, v[40:41], off nt
	global_load_dword v69, v[42:43], off nt
	global_load_dword v70, v[44:45], off nt
	global_load_dword v71, v[46:47], off nt
	global_load_dword v72, v[48:49], off nt
	v_add_co_u32_e32 v34, vcc, 0x30000, v32
	s_nop 1
	v_addc_co_u32_e32 v35, vcc, 0, v33, vcc
	v_add_co_u32_e32 v36, vcc, 0x32000, v32
	s_nop 1
	v_addc_co_u32_e32 v37, vcc, 0, v33, vcc
	v_add_co_u32_e32 v38, vcc, 0x34000, v32
	s_nop 1
	v_addc_co_u32_e32 v39, vcc, 0, v33, vcc
	v_add_co_u32_e32 v40, vcc, 0x36000, v32
	s_nop 1
	v_addc_co_u32_e32 v41, vcc, 0, v33, vcc
	v_add_co_u32_e32 v42, vcc, 0x38000, v32
	s_nop 1
	v_addc_co_u32_e32 v43, vcc, 0, v33, vcc
	v_add_co_u32_e32 v44, vcc, 0x3a000, v32
	s_nop 1
	v_addc_co_u32_e32 v45, vcc, 0, v33, vcc
	v_add_co_u32_e32 v46, vcc, 0x3c000, v32
	s_nop 1
	v_addc_co_u32_e32 v47, vcc, 0, v33, vcc
	v_add_co_u32_e32 v32, vcc, 0x3e000, v32
	s_nop 1
	v_addc_co_u32_e32 v33, vcc, 0, v33, vcc
	global_load_dword v48, v[34:35], off nt
	global_load_dword v49, v[36:37], off nt
	global_load_dword v73, v[38:39], off nt
	global_load_dword v74, v[40:41], off nt
	global_load_dword v75, v[42:43], off nt
	global_load_dword v76, v[44:45], off nt
	global_load_dword v77, v[46:47], off nt
	global_load_dword v78, v[32:33], off nt
	s_waitcnt vmcnt(0)
	ds_write2_b32 v18, v31, v50 offset1:66
	ds_write2_b32 v18, v51, v52 offset0:132 offset1:198
	ds_write2_b32 v24, v53, v54 offset0:8 offset1:74
	ds_write2_b32 v24, v55, v56 offset0:140 offset1:206
	ds_write2_b32 v25, v57, v58 offset0:16 offset1:82
	ds_write2_b32 v25, v59, v60 offset0:148 offset1:214
	ds_write2_b32 v26, v61, v62 offset0:24 offset1:90
	ds_write2_b32 v26, v63, v64 offset0:156 offset1:222
	ds_write2_b32 v27, v65, v66 offset0:32 offset1:98
	ds_write2_b32 v27, v67, v68 offset0:164 offset1:230
	ds_write2_b32 v28, v69, v70 offset0:40 offset1:106
	ds_write2_b32 v28, v71, v72 offset0:172 offset1:238
	ds_write2_b32 v29, v48, v49 offset0:48 offset1:114
	ds_write2_b32 v29, v73, v74 offset0:180 offset1:246
	ds_write2_b32 v30, v75, v76 offset0:56 offset1:122
	ds_write2_b32 v30, v77, v78 offset0:188 offset1:254
	s_waitcnt lgkmcnt(0)
	ds_read2_b32 v[36:37], v20 offset0:33 offset1:41
	ds_read2_b32 v[38:39], v20 offset1:8
	ds_read2_b32 v[40:41], v20 offset0:66 offset1:74
	ds_read2_b32 v[42:43], v20 offset0:99 offset1:107
	ds_read2_b32 v[44:45], v20 offset0:132 offset1:140
	ds_read2_b32 v[46:47], v20 offset0:165 offset1:173
	ds_read2_b32 v[48:49], v20 offset0:198 offset1:206
	ds_read2_b32 v[50:51], v20 offset0:231 offset1:239
	v_add_u32_e32 v54, s17, v19
	v_ashrrev_i32_e32 v55, 31, v54
	v_lshl_add_u64 v[52:53], s[8:9], 1, v[10:11]
	v_lshlrev_b64 v[54:55], 11, v[54:55]
	s_waitcnt lgkmcnt(6)
	v_cvt_pk_bf16_f32 v32, v38, v36
	s_waitcnt lgkmcnt(4)
	v_cvt_pk_bf16_f32 v33, v40, v42
	s_waitcnt lgkmcnt(2)
	v_cvt_pk_bf16_f32 v34, v44, v46
	s_waitcnt lgkmcnt(0)
	v_cvt_pk_bf16_f32 v35, v48, v50
	v_lshl_add_u64 v[54:55], v[52:53], 0, v[54:55]
	v_add_u32_e32 v36, s17, v21
	global_store_dwordx4 v[54:55], v[32:35], off sc1
	s_nop 1
	v_cvt_pk_bf16_f32 v32, v39, v37
	v_ashrrev_i32_e32 v37, 31, v36
	v_cvt_pk_bf16_f32 v33, v41, v43
	v_cvt_pk_bf16_f32 v34, v45, v47
	v_cvt_pk_bf16_f32 v35, v49, v51
	v_lshlrev_b64 v[36:37], 11, v[36:37]
	ds_read2_b32 v[38:39], v20 offset0:49 offset1:57
	ds_read2_b32 v[40:41], v20 offset0:16 offset1:24
	ds_read2_b32 v[42:43], v20 offset0:82 offset1:90
	ds_read2_b32 v[44:45], v20 offset0:115 offset1:123
	ds_read2_b32 v[46:47], v20 offset0:148 offset1:156
	ds_read2_b32 v[48:49], v20 offset0:181 offset1:189
	ds_read2_b32 v[50:51], v20 offset0:214 offset1:222
	ds_read2_b32 v[54:55], v20 offset0:247 offset1:255
	v_lshl_add_u64 v[36:37], v[52:53], 0, v[36:37]
	global_store_dwordx4 v[36:37], v[32:35], off sc1
	v_add_u32_e32 v36, s17, v22
	v_ashrrev_i32_e32 v37, 31, v36
	v_lshlrev_b64 v[36:37], 11, v[36:37]
	s_waitcnt lgkmcnt(6)
	v_cvt_pk_bf16_f32 v32, v40, v38
	s_waitcnt lgkmcnt(4)
	v_cvt_pk_bf16_f32 v33, v42, v44
	s_waitcnt lgkmcnt(2)
	v_cvt_pk_bf16_f32 v34, v46, v48
	s_waitcnt lgkmcnt(0)
	v_cvt_pk_bf16_f32 v35, v50, v54
	v_lshl_add_u64 v[36:37], v[52:53], 0, v[36:37]
	global_store_dwordx4 v[36:37], v[32:35], off sc1
	v_add_u32_e32 v36, s17, v23
	v_ashrrev_i32_e32 v37, 31, v36
	v_lshlrev_b64 v[36:37], 11, v[36:37]
	v_cvt_pk_bf16_f32 v32, v41, v39
	v_cvt_pk_bf16_f32 v33, v43, v45
	v_cvt_pk_bf16_f32 v34, v47, v49
	v_cvt_pk_bf16_f32 v35, v51, v55
	v_lshl_add_u64 v[36:37], v[52:53], 0, v[36:37]
	global_store_dwordx4 v[36:37], v[32:35], off sc1
	s_waitcnt lgkmcnt(0)

.LBB0_561:
	s_waitcnt vmcnt(0)
	v_sub_u32_e32 v0, 0, v16
	v_cmp_eq_u32_e32 vcc, s76, v0
	s_waitcnt vmcnt(0) lgkmcnt(0)
	s_barrier
	s_and_saveexec_b64 s[6:7], vcc
	s_cbranch_execz .LBB0_564
	s_mov_b64 s[8:9], exec
	v_mbcnt_lo_u32_b32 v0, s8, 0
	v_mbcnt_hi_u32_b32 v0, s9, v0
	v_cmp_eq_u32_e32 vcc, 0, v0
	s_and_b64 s[10:11], exec, vcc
	s_nop 0
	s_mov_b64 exec, s[10:11]
	s_cbranch_execz .LBB0_564
	s_bcnt1_i32_b64 s3, s[8:9]
	v_mov_b32_e32 v0, 0x28000
	v_mov_b32_e32 v1, s3
	global_atomic_add v0, v1, s[4:5] offset:512
